# attention PV: V tile rows stored in natural key order, 8 v_permlane32_swap per tile removed (P fragment order matches accumulator)
# speedup vs baseline: 1.0051x; 1.0051x over previous
.LBB0_509:
	s_xor_b64 s[18:19], s[4:5], -1
	s_lshl_b64 s[4:5], s[0:1], 1
	s_add_u32 s22, s56, s4
	s_addc_u32 s23, s57, s5
	v_mov_b32_e32 v2, v208
	s_add_u32 s0, s58, s4
	s_addc_u32 s1, s59, s5
	v_readfirstlane_b32 s20, v2
	s_ashr_i32 s24, s20, 6
	s_and_b32 s20, s20, 0x3fffffc0
	s_lshl_b32 s20, s20, 2
	v_and_b32_e32 v219, 31, v2
	s_add_i32 s21, s20, 0
	s_lshl_b32 s20, s24, 5
	v_or_b32_e32 v0, s20, v219
	s_waitcnt lgkmcnt(0)
	v_ashrrev_i32_e32 v1, 31, v0
	v_bfe_u32 v218, v2, 5, 1
	v_lshlrev_b64 v[0:1], 11, v[0:1]
	v_lshl_add_u64 v[0:1], s[22:23], 0, v[0:1]
	v_lshlrev_b32_e32 v210, 4, v218
	v_lshl_add_u64 v[0:1], v[0:1], 0, v[210:211]
	global_load_dwordx4 v[160:163], v[0:1], off
	global_load_dwordx4 v[164:167], v[0:1], off offset:32
	global_load_dwordx4 v[168:171], v[0:1], off offset:64
	global_load_dwordx4 v[172:175], v[0:1], off offset:96
	global_load_dwordx4 v[176:179], v[0:1], off offset:128
	global_load_dwordx4 v[180:183], v[0:1], off offset:160
	global_load_dwordx4 v[184:187], v[0:1], off offset:192
	global_load_dwordx4 v[188:191], v[0:1], off offset:224
	s_lshl_b32 s22, s24, 3
	v_bfe_u32 v1, v2, 4, 2
	v_or_b32_e32 v0, s22, v1
	v_bitop3_b32 v4, v1, v2, 15 bitop3:0x78
	v_ashrrev_i32_e32 v1, 31, v0
	v_lshlrev_b64 v[212:213], 10, v[0:1]
	v_or_b32_e32 v0, 4, v0
	v_and_b32_e32 v3, 15, v2
	v_ashrrev_i32_e32 v1, 31, v0
	v_bitop3_b32 v3, v0, v3, 7 bitop3:0x6c
	v_lshlrev_b64 v[214:215], 10, v[0:1]
	v_bfe_u32 v0, v2, 2, 3
	v_bitop3_b32 v0, s22, -13, v0 bitop3:0xc8
	v_lshrrev_b32_e32 v1, 2, v2
	s_lshl_b32 s22, s24, 3
	v_and_b32_e32 v1, 4, v1
	s_and_b32 s22, s22, 8
	v_or3_b32 v0, v0, v1, s22
	s_add_i32 s21, s21, 0x24000
	v_ashrrev_i32_e32 v1, 31, v0
	v_lshlrev_b32_e32 v11, 3, v2
	s_lshl_b32 s22, s24, 11
	v_lshl_or_b32 v212, v4, 3, v212
	v_lshlrev_b64 v[216:217], 10, v[0:1]
	v_and_b32_e32 v0, 32, v2
	v_and_b32_e32 v1, 24, v11
	s_cmp_lg_u32 0, -1
	v_or3_b32 v216, v216, v1, v0
	v_lshlrev_b64 v[0:1], 1, v[212:213]
	s_cselect_b32 s23, 0, 0
	v_and_b32_e32 v10, 63, v2
	v_lshl_or_b32 v214, v3, 3, v214
	v_lshlrev_b32_e32 v12, 4, v2
	v_lshlrev_b32_e32 v13, 1, v2
	v_lshl_add_u64 v[2:3], s[0:1], 0, v[0:1]
	s_add_i32 s75, s22, s23
	s_mov_b32 s25, m0
	s_mov_b32 m0, s75
	s_nop 0
	global_load_lds_dwordx4 v[2:3], off
	s_mov_b32 m0, s25
	v_lshlrev_b64 v[2:3], 1, v[214:215]
	s_or_b32 s25, s22, 0x400
	v_lshl_add_u64 v[4:5], s[0:1], 0, v[2:3]
	s_add_i32 s77, s25, s23
	s_mov_b32 s84, m0
	s_mov_b32 m0, s77
	s_nop 0
	global_load_lds_dwordx4 v[4:5], off
	s_mov_b32 m0, s84
	s_lshl_b32 s24, s24, 12
	v_lshlrev_b64 v[4:5], 1, v[216:217]
	s_add_i32 s84, s23, 0xc000
	v_lshl_add_u64 v[6:7], s[14:15], 0, v[4:5]
	s_add_i32 s77, s24, s84
	s_mov_b32 s85, m0
	s_mov_b32 m0, s77
	s_nop 0
	global_load_lds_dwordx4 v[6:7], off
	s_mov_b32 m0, s85
	s_or_b32 s85, s24, 0x400
	s_add_i32 s86, s85, s84
	v_lshl_add_u64 v[8:9], v[6:7], 0, s[8:9]
	s_mov_b32 s87, m0
	s_mov_b32 m0, s86
	s_nop 0
	global_load_lds_dwordx4 v[8:9], off
	s_mov_b32 m0, s87
	s_or_b32 s86, s24, 0x800
	s_add_i32 s87, s86, s84
	v_lshl_add_u64 v[8:9], v[6:7], 0, s[10:11]
	s_mov_b32 s96, m0
	s_mov_b32 m0, s87
	s_nop 0
	global_load_lds_dwordx4 v[8:9], off
	s_mov_b32 m0, s96
	s_or_b32 s87, s24, 0xc00
	s_add_i32 s96, s87, s84
	s_add_u32 s0, s0, 0x20000
	v_lshl_add_u64 v[6:7], v[6:7], 0, s[12:13]
	s_mov_b32 s97, m0
	s_mov_b32 m0, s96
	s_nop 0
	global_load_lds_dwordx4 v[6:7], off
	s_mov_b32 m0, s97
	s_addc_u32 s1, s1, 0
	s_add_i32 s96, s23, 0x4000
	v_lshl_add_u64 v[0:1], s[0:1], 0, v[0:1]
	s_add_i32 s22, s22, s96
	s_mov_b32 s97, m0
	s_mov_b32 m0, s22
	s_nop 0
	global_load_lds_dwordx4 v[0:1], off
	s_mov_b32 m0, s97
	v_lshl_add_u64 v[0:1], s[0:1], 0, v[2:3]
	s_add_i32 s25, s25, s96
	s_mov_b32 s0, m0
	s_mov_b32 m0, s25
	s_nop 0
	global_load_lds_dwordx4 v[0:1], off
	s_mov_b32 m0, s0
	s_add_i32 s23, s23, 0x14000
	v_lshl_add_u64 v[0:1], s[16:17], 0, v[4:5]
	s_add_i32 s24, s24, s23
	s_mov_b32 s0, m0
	s_mov_b32 m0, s24
	s_nop 0
	global_load_lds_dwordx4 v[0:1], off
	s_mov_b32 m0, s0
	v_lshl_add_u64 v[2:3], v[0:1], 0, s[8:9]
	s_add_i32 s85, s85, s23
	s_mov_b32 s0, m0
	s_mov_b32 m0, s85
	s_nop 0
	global_load_lds_dwordx4 v[2:3], off
	s_mov_b32 m0, s0
	v_lshl_add_u64 v[2:3], v[0:1], 0, s[10:11]
	s_add_i32 s86, s86, s23
	s_mov_b32 s0, m0
	s_mov_b32 m0, s86
	s_nop 0
	global_load_lds_dwordx4 v[2:3], off
	s_mov_b32 m0, s0
	v_lshl_add_u64 v[0:1], v[0:1], 0, s[12:13]
	s_add_i32 s87, s87, s23
	s_mov_b32 s0, m0
	s_mov_b32 m0, s87
	s_nop 0
	global_load_lds_dwordx4 v[0:1], off
	s_mov_b32 m0, s0
	s_movk_i32 s0, 0x70
	v_and_b32_e32 v1, 0x70, v12
	v_bitop3_b32 v221, v210, v12, s0 bitop3:0x78
	s_movk_i32 s0, 0x60
	v_bitop3_b32 v224, v210, v1, s0 bitop3:0x36
	s_movk_i32 s0, 0x80
	v_and_b32_e32 v0, 0x118, v11
	v_bitop3_b32 v225, v210, v1, s0 bitop3:0x36
	s_movk_i32 s0, 0xa0
	v_and_b32_e32 v14, 0xc0, v12
	v_bitop3_b32 v227, v210, v1, s0 bitop3:0x36
	s_movk_i32 s0, 0xc0
	v_and_or_b32 v0, v13, 32, v0
	v_bitop3_b32 v228, v210, v1, s0 bitop3:0x36
	s_movk_i32 s0, 0xe0
	v_add3_u32 v230, v14, s84, v0
	v_mov_b32_e32 v14, v211
	v_mov_b32_e32 v15, v211
	v_bitop3_b32 v222, v210, v1, 32 bitop3:0x36
	v_bitop3_b32 v223, v210, v1, 64 bitop3:0x36
	v_bitop3_b32 v229, v210, v1, s0 bitop3:0x36
	v_cmp_gt_u32_e64 s[0:1], 32, v10
	s_add_u32 s84, s66, s4
	v_mov_b32_e32 v0, v211
	v_mov_b32_e32 v1, v211
	v_mov_b32_e32 v2, v211
	v_mov_b32_e32 v3, v211
	v_mov_b32_e32 v4, v211
	v_mov_b32_e32 v5, v211
	v_mov_b32_e32 v6, v211
	v_mov_b32_e32 v7, v211
	v_mov_b32_e32 v8, v211
	v_mov_b32_e32 v9, v211
	v_mov_b32_e32 v10, v211
	v_mov_b32_e32 v11, v211
	v_mov_b32_e32 v12, v211
	v_mov_b32_e32 v13, v211
	v_mov_b64_e32 v[126:127], v[14:15]
	v_mov_b64_e32 v[110:111], v[14:15]
	v_mov_b64_e32 v[94:95], v[14:15]
	v_mov_b64_e32 v[78:79], v[14:15]
	v_mov_b64_e32 v[62:63], v[14:15]
	v_mov_b64_e32 v[46:47], v[14:15]
	v_mov_b64_e32 v[30:31], v[14:15]
	s_mov_b32 s74, 2
	s_mov_b32 s76, 0
	v_lshlrev_b32_e32 v220, 8, v219
	v_lshl_add_u32 v226, v219, 2, s21
	s_addc_u32 s85, s67, s5
	v_mov_b32_e32 v232, 0
	v_mov_b32_e32 v231, 0xf149f2ca
	s_mov_b64 s[22:23], 0
	v_mov_b64_e32 v[124:125], v[12:13]
	v_mov_b64_e32 v[122:123], v[10:11]
	v_mov_b64_e32 v[120:121], v[8:9]
	v_mov_b64_e32 v[118:119], v[6:7]
	v_mov_b64_e32 v[116:117], v[4:5]
	v_mov_b64_e32 v[114:115], v[2:3]
	v_mov_b64_e32 v[112:113], v[0:1]
	v_mov_b64_e32 v[108:109], v[12:13]
	v_mov_b64_e32 v[106:107], v[10:11]
	v_mov_b64_e32 v[104:105], v[8:9]
	v_mov_b64_e32 v[102:103], v[6:7]
	v_mov_b64_e32 v[100:101], v[4:5]
	v_mov_b64_e32 v[98:99], v[2:3]
	v_mov_b64_e32 v[96:97], v[0:1]
	v_mov_b64_e32 v[92:93], v[12:13]
	v_mov_b64_e32 v[90:91], v[10:11]
	v_mov_b64_e32 v[88:89], v[8:9]
	v_mov_b64_e32 v[86:87], v[6:7]
	v_mov_b64_e32 v[84:85], v[4:5]
	v_mov_b64_e32 v[82:83], v[2:3]
	v_mov_b64_e32 v[80:81], v[0:1]
	v_mov_b64_e32 v[76:77], v[12:13]
	v_mov_b64_e32 v[74:75], v[10:11]
	v_mov_b64_e32 v[72:73], v[8:9]
	v_mov_b64_e32 v[70:71], v[6:7]
	v_mov_b64_e32 v[68:69], v[4:5]
	v_mov_b64_e32 v[66:67], v[2:3]
	v_mov_b64_e32 v[64:65], v[0:1]
	v_mov_b64_e32 v[60:61], v[12:13]
	v_mov_b64_e32 v[58:59], v[10:11]
	v_mov_b64_e32 v[56:57], v[8:9]
	v_mov_b64_e32 v[54:55], v[6:7]
	v_mov_b64_e32 v[52:53], v[4:5]
	v_mov_b64_e32 v[50:51], v[2:3]
	v_mov_b64_e32 v[48:49], v[0:1]
	v_mov_b64_e32 v[44:45], v[12:13]
	v_mov_b64_e32 v[42:43], v[10:11]
	v_mov_b64_e32 v[40:41], v[8:9]
	v_mov_b64_e32 v[38:39], v[6:7]
	v_mov_b64_e32 v[36:37], v[4:5]
	v_mov_b64_e32 v[34:35], v[2:3]
	v_mov_b64_e32 v[32:33], v[0:1]
	v_mov_b64_e32 v[28:29], v[12:13]
	v_mov_b64_e32 v[26:27], v[10:11]
	v_mov_b64_e32 v[24:25], v[8:9]
	v_mov_b64_e32 v[22:23], v[6:7]
	v_mov_b64_e32 v[20:21], v[4:5]
	v_mov_b64_e32 v[18:19], v[2:3]
	v_mov_b64_e32 v[16:17], v[0:1]
	s_mov_b32 s86, 0
	s_cmp_eq_u32 s22, 0x7e0000
	s_mov_b64 s[4:5], -1
	s_cbranch_scc0 .LBB0_519

.LBB0_517:
	v_cndmask_b32_e64 v231, v234, v231, s[4:5]
	v_mul_f32_e32 v192, 0xbe0293ee, v231
	v_fmamk_f32 v144, v144, 0x3e0293ee, v192
	v_fmamk_f32 v145, v145, 0x3e0293ee, v192
	v_fmamk_f32 v146, v146, 0x3e0293ee, v192
	v_fmamk_f32 v147, v147, 0x3e0293ee, v192
	v_fmamk_f32 v148, v148, 0x3e0293ee, v192
	v_fmamk_f32 v149, v149, 0x3e0293ee, v192
	v_fmamk_f32 v150, v150, 0x3e0293ee, v192
	v_fmamk_f32 v151, v151, 0x3e0293ee, v192
	v_fmamk_f32 v152, v152, 0x3e0293ee, v192
	v_fmamk_f32 v153, v153, 0x3e0293ee, v192
	v_fmamk_f32 v154, v154, 0x3e0293ee, v192
	v_fmamk_f32 v155, v155, 0x3e0293ee, v192
	v_fmamk_f32 v156, v156, 0x3e0293ee, v192
	v_fmamk_f32 v157, v157, 0x3e0293ee, v192
	v_fmamk_f32 v158, v158, 0x3e0293ee, v192
	v_fmamk_f32 v159, v159, 0x3e0293ee, v192
	v_fmamk_f32 v128, v128, 0x3e0293ee, v192
	v_fmamk_f32 v129, v129, 0x3e0293ee, v192
	v_fmamk_f32 v130, v130, 0x3e0293ee, v192
	v_fmamk_f32 v131, v131, 0x3e0293ee, v192
	v_fmamk_f32 v132, v132, 0x3e0293ee, v192
	v_fmamk_f32 v133, v133, 0x3e0293ee, v192
	v_fmamk_f32 v134, v134, 0x3e0293ee, v192
	v_fmamk_f32 v135, v135, 0x3e0293ee, v192
	v_fmamk_f32 v136, v136, 0x3e0293ee, v192
	v_fmamk_f32 v137, v137, 0x3e0293ee, v192
	v_fmamk_f32 v138, v138, 0x3e0293ee, v192
	v_fmamk_f32 v139, v139, 0x3e0293ee, v192
	v_fmamk_f32 v140, v140, 0x3e0293ee, v192
	v_fmamk_f32 v141, v141, 0x3e0293ee, v192
	v_fmamk_f32 v142, v142, 0x3e0293ee, v192
	v_fmac_f32_e32 v192, 0x3e0293ee, v143
	v_exp_f32_e32 v143, v144
	v_exp_f32_e32 v145, v145
	v_exp_f32_e32 v146, v146
	v_exp_f32_e32 v147, v147
	v_exp_f32_e32 v148, v148
	v_exp_f32_e32 v193, v128
	v_exp_f32_e32 v149, v149
	v_add_f32_e32 v128, v145, v143
	v_exp_f32_e32 v150, v150
	v_add_f32_e32 v128, v146, v128
	v_exp_f32_e32 v151, v151
	v_add_f32_e32 v128, v147, v128
	v_exp_f32_e32 v152, v152
	v_add_f32_e32 v128, v148, v128
	v_exp_f32_e32 v153, v153
	v_add_f32_e32 v128, v149, v128
	v_exp_f32_e32 v154, v154
	v_add_f32_e32 v128, v150, v128
	v_exp_f32_e32 v155, v155
	v_add_f32_e32 v128, v151, v128
	v_exp_f32_e32 v156, v156
	v_add_f32_e32 v128, v152, v128
	v_exp_f32_e32 v157, v157
	v_add_f32_e32 v128, v153, v128
	v_exp_f32_e32 v158, v158
	v_add_f32_e32 v128, v154, v128
	v_exp_f32_e32 v159, v159
	v_add_f32_e32 v128, v155, v128
	v_add_f32_e32 v128, v156, v128
	v_exp_f32_e32 v194, v129
	v_add_f32_e32 v128, v157, v128
	v_exp_f32_e32 v195, v130
	v_add_f32_e32 v128, v158, v128
	v_exp_f32_e32 v196, v131
	v_add_f32_e32 v128, v159, v128
	v_exp_f32_e32 v197, v132
	v_add_f32_e32 v128, v193, v128
	v_exp_f32_e32 v198, v133
	v_add_f32_e32 v128, v194, v128
	v_exp_f32_e32 v199, v134
	v_add_f32_e32 v128, v195, v128
	v_exp_f32_e32 v135, v135
	v_add_f32_e32 v128, v196, v128
	v_exp_f32_e32 v200, v136
	v_add_f32_e32 v128, v197, v128
	v_exp_f32_e32 v201, v137
	v_add_f32_e32 v128, v198, v128
	v_exp_f32_e32 v202, v138
	v_add_f32_e32 v128, v199, v128
	v_exp_f32_e32 v203, v139
	v_add_f32_e32 v128, v135, v128
	v_exp_f32_e32 v204, v140
	v_add_f32_e32 v128, v200, v128
	v_exp_f32_e32 v205, v141
	v_add_f32_e32 v128, v201, v128
	v_exp_f32_e32 v206, v142
	v_add_f32_e32 v128, v202, v128
	v_exp_f32_e32 v192, v192
	v_add_f32_e32 v128, v203, v128
	v_add_f32_e32 v128, v204, v128
	v_add_f32_e32 v128, v205, v128
	v_add_f32_e32 v128, v206, v128
	v_add_f32_e32 v128, v192, v128
	v_mov_b32_e32 v129, v128
	s_nop 1
	v_permlane32_swap_b32_e32 v128, v129
	v_add_f32_e32 v144, v128, v129
	v_fmac_f32_e32 v144, v232, v233
	v_cvt_pk_bf16_f32 v128, v143, v145
	v_cvt_pk_bf16_f32 v129, v146, v147
	v_cvt_pk_bf16_f32 v130, v148, v149
	v_cvt_pk_bf16_f32 v131, v150, v151
	v_cvt_pk_bf16_f32 v136, v152, v153
	v_cvt_pk_bf16_f32 v137, v154, v155
	v_cvt_pk_bf16_f32 v138, v156, v157
	v_cvt_pk_bf16_f32 v139, v158, v159
	v_cvt_pk_bf16_f32 v132, v193, v194
	v_cvt_pk_bf16_f32 v133, v195, v196
	v_cvt_pk_bf16_f32 v134, v197, v198
	v_cvt_pk_bf16_f32 v135, v199, v135
	v_cvt_pk_bf16_f32 v140, v200, v201
	v_cvt_pk_bf16_f32 v141, v202, v203
	v_cvt_pk_bf16_f32 v142, v204, v205
	v_cvt_pk_bf16_f32 v143, v206, v192
	v_lshl_add_u32 v145, s76, 15, v230
	ds_read_b64_tr_b16 v[146:147], v145 offset:0
	ds_read_b64_tr_b16 v[148:149], v145 offset:0x1000
	ds_read_b64_tr_b16 v[150:151], v145 offset:0x2000
	ds_read_b64_tr_b16 v[152:153], v145 offset:0x3000
	ds_read_b64_tr_b16 v[154:155], v145 offset:0x4000
	ds_read_b64_tr_b16 v[156:157], v145 offset:0x5000
	ds_read_b64_tr_b16 v[192:193], v145 offset:0x6000
	ds_read_b64_tr_b16 v[194:195], v145 offset:0x7000
	ds_read_b64_tr_b16 v[196:197], v145 offset:0x200
	ds_read_b64_tr_b16 v[198:199], v145 offset:0x1200
	ds_read_b64_tr_b16 v[200:201], v145 offset:0x2200
	ds_read_b64_tr_b16 v[202:203], v145 offset:0x3200
	ds_read_b64_tr_b16 v[204:205], v145 offset:0x4200
	ds_read_b64_tr_b16 v[206:207], v145 offset:0x5200
	ds_read_b64_tr_b16 v[232:233], v145 offset:0x6200
	ds_read_b64_tr_b16 v[234:235], v145 offset:0x7200
	s_waitcnt lgkmcnt(8)
	s_nop 0
	v_mfma_f32_32x32x16_bf16 v[0:15], v[128:131], v[146:149], v[0:15]
	v_mfma_f32_32x32x16_bf16 v[0:15], v[136:139], v[150:153], v[0:15]
	v_mfma_f32_32x32x16_bf16 v[0:15], v[132:135], v[154:157], v[0:15]
	v_mfma_f32_32x32x16_bf16 v[0:15], v[140:143], v[192:195], v[0:15]
	ds_read_b64_tr_b16 v[146:147], v145 offset:0x400
	ds_read_b64_tr_b16 v[148:149], v145 offset:0x1400
	ds_read_b64_tr_b16 v[150:151], v145 offset:0x2400
	ds_read_b64_tr_b16 v[152:153], v145 offset:0x3400
	ds_read_b64_tr_b16 v[154:155], v145 offset:0x4400
	ds_read_b64_tr_b16 v[156:157], v145 offset:0x5400
	ds_read_b64_tr_b16 v[192:193], v145 offset:0x6400
	ds_read_b64_tr_b16 v[194:195], v145 offset:0x7400
	s_waitcnt lgkmcnt(8)
	v_mfma_f32_32x32x16_bf16 v[112:127], v[128:131], v[196:199], v[112:127]
	v_mfma_f32_32x32x16_bf16 v[112:127], v[136:139], v[200:203], v[112:127]
	v_mfma_f32_32x32x16_bf16 v[112:127], v[132:135], v[204:207], v[112:127]
	v_mfma_f32_32x32x16_bf16 v[112:127], v[140:143], v[232:235], v[112:127]
	ds_read_b64_tr_b16 v[196:197], v145 offset:0x600
	ds_read_b64_tr_b16 v[198:199], v145 offset:0x1600
	ds_read_b64_tr_b16 v[200:201], v145 offset:0x2600
	ds_read_b64_tr_b16 v[202:203], v145 offset:0x3600
	ds_read_b64_tr_b16 v[204:205], v145 offset:0x4600
	ds_read_b64_tr_b16 v[206:207], v145 offset:0x5600
	ds_read_b64_tr_b16 v[232:233], v145 offset:0x6600
	ds_read_b64_tr_b16 v[234:235], v145 offset:0x7600
	s_waitcnt lgkmcnt(8)
	v_mfma_f32_32x32x16_bf16 v[96:111], v[128:131], v[146:149], v[96:111]
	v_mfma_f32_32x32x16_bf16 v[96:111], v[136:139], v[150:153], v[96:111]
	v_mfma_f32_32x32x16_bf16 v[96:111], v[132:135], v[154:157], v[96:111]
	v_mfma_f32_32x32x16_bf16 v[96:111], v[140:143], v[192:195], v[96:111]
	ds_read_b64_tr_b16 v[146:147], v145 offset:0x800
	ds_read_b64_tr_b16 v[148:149], v145 offset:0x1800
	ds_read_b64_tr_b16 v[150:151], v145 offset:0x2800
	ds_read_b64_tr_b16 v[152:153], v145 offset:0x3800
	ds_read_b64_tr_b16 v[154:155], v145 offset:0x4800
	ds_read_b64_tr_b16 v[156:157], v145 offset:0x5800
	ds_read_b64_tr_b16 v[192:193], v145 offset:0x6800
	ds_read_b64_tr_b16 v[194:195], v145 offset:0x7800
	s_waitcnt lgkmcnt(8)
	v_mfma_f32_32x32x16_bf16 v[80:95], v[128:131], v[196:199], v[80:95]
	v_mfma_f32_32x32x16_bf16 v[80:95], v[136:139], v[200:203], v[80:95]
	v_mfma_f32_32x32x16_bf16 v[80:95], v[132:135], v[204:207], v[80:95]
	v_mfma_f32_32x32x16_bf16 v[80:95], v[140:143], v[232:235], v[80:95]
	ds_read_b64_tr_b16 v[196:197], v145 offset:0xa00
	ds_read_b64_tr_b16 v[198:199], v145 offset:0x1a00
	ds_read_b64_tr_b16 v[200:201], v145 offset:0x2a00
	ds_read_b64_tr_b16 v[202:203], v145 offset:0x3a00
	ds_read_b64_tr_b16 v[204:205], v145 offset:0x4a00
	ds_read_b64_tr_b16 v[206:207], v145 offset:0x5a00
	ds_read_b64_tr_b16 v[232:233], v145 offset:0x6a00
	ds_read_b64_tr_b16 v[234:235], v145 offset:0x7a00
	s_waitcnt lgkmcnt(8)
	v_mfma_f32_32x32x16_bf16 v[64:79], v[128:131], v[146:149], v[64:79]
	v_mfma_f32_32x32x16_bf16 v[64:79], v[136:139], v[150:153], v[64:79]
	v_mfma_f32_32x32x16_bf16 v[64:79], v[132:135], v[154:157], v[64:79]
	v_mfma_f32_32x32x16_bf16 v[64:79], v[140:143], v[192:195], v[64:79]
	ds_read_b64_tr_b16 v[146:147], v145 offset:0xc00
	ds_read_b64_tr_b16 v[148:149], v145 offset:0x1c00
	ds_read_b64_tr_b16 v[150:151], v145 offset:0x2c00
	ds_read_b64_tr_b16 v[152:153], v145 offset:0x3c00
	ds_read_b64_tr_b16 v[154:155], v145 offset:0x4c00
	ds_read_b64_tr_b16 v[156:157], v145 offset:0x5c00
	ds_read_b64_tr_b16 v[192:193], v145 offset:0x6c00
	ds_read_b64_tr_b16 v[194:195], v145 offset:0x7c00
	s_waitcnt lgkmcnt(8)
	v_mfma_f32_32x32x16_bf16 v[48:63], v[128:131], v[196:199], v[48:63]
	v_mfma_f32_32x32x16_bf16 v[48:63], v[136:139], v[200:203], v[48:63]
	v_mfma_f32_32x32x16_bf16 v[48:63], v[132:135], v[204:207], v[48:63]
	v_mfma_f32_32x32x16_bf16 v[48:63], v[140:143], v[232:235], v[48:63]
	ds_read_b64_tr_b16 v[196:197], v145 offset:0xe00
	ds_read_b64_tr_b16 v[198:199], v145 offset:0x1e00
	ds_read_b64_tr_b16 v[200:201], v145 offset:0x2e00
	ds_read_b64_tr_b16 v[202:203], v145 offset:0x3e00
	ds_read_b64_tr_b16 v[204:205], v145 offset:0x4e00
	ds_read_b64_tr_b16 v[206:207], v145 offset:0x5e00
	ds_read_b64_tr_b16 v[232:233], v145 offset:0x6e00
	ds_read_b64_tr_b16 v[234:235], v145 offset:0x7e00
	s_waitcnt lgkmcnt(8)
	v_mfma_f32_32x32x16_bf16 v[32:47], v[128:131], v[146:149], v[32:47]
	v_mfma_f32_32x32x16_bf16 v[32:47], v[136:139], v[150:153], v[32:47]
	v_mfma_f32_32x32x16_bf16 v[32:47], v[132:135], v[154:157], v[32:47]
	v_mfma_f32_32x32x16_bf16 v[32:47], v[140:143], v[192:195], v[32:47]
	s_waitcnt lgkmcnt(0)
	v_mfma_f32_32x32x16_bf16 v[16:31], v[128:131], v[196:199], v[16:31]
	s_add_i32 s4, s76, 1
	s_cmp_lg_u32 s76, 2
	s_cselect_b32 s76, s4, 0
	s_add_i32 s4, s74, 1
	s_cmp_lg_u32 s74, 2
	s_cselect_b32 s74, s4, 0
	s_add_u32 s22, s22, 0x20000
	v_mfma_f32_32x32x16_bf16 v[16:31], v[136:139], v[200:203], v[16:31]
	s_addc_u32 s23, s23, 0
	s_add_i32 s86, s86, 1
	s_cmp_eq_u32 s22, 0x800000
	v_mfma_f32_32x32x16_bf16 v[16:31], v[132:135], v[204:207], v[16:31]
	v_mfma_f32_32x32x16_bf16 v[16:31], v[140:143], v[232:235], v[16:31]
	s_cbranch_scc1 .LBB0_521
	v_mov_b32_e32 v232, v144
	s_cmp_eq_u32 s22, 0x7e0000
	s_mov_b64 s[4:5], -1
	s_cbranch_scc1 .LBB0_510

.LBB0_902:
	s_xor_b64 s[18:19], s[4:5], -1
	s_lshl_b64 s[4:5], s[0:1], 1
	s_add_u32 s22, s62, s4
	s_addc_u32 s23, s63, s5
	v_mov_b32_e32 v2, v208
	s_add_u32 s0, s64, s4
	s_addc_u32 s1, s65, s5
	v_readfirstlane_b32 s20, v2
	s_ashr_i32 s24, s20, 6
	s_and_b32 s20, s20, 0x3fffffc0
	s_lshl_b32 s20, s20, 2
	v_and_b32_e32 v219, 31, v2
	s_add_i32 s21, s20, 0
	s_lshl_b32 s20, s24, 5
	v_or_b32_e32 v0, s20, v219
	s_waitcnt lgkmcnt(0)
	v_ashrrev_i32_e32 v1, 31, v0
	v_bfe_u32 v218, v2, 5, 1
	v_lshlrev_b64 v[0:1], 11, v[0:1]
	v_lshl_add_u64 v[0:1], s[22:23], 0, v[0:1]
	v_lshlrev_b32_e32 v210, 4, v218
	v_lshl_add_u64 v[0:1], v[0:1], 0, v[210:211]
	global_load_dwordx4 v[160:163], v[0:1], off
	global_load_dwordx4 v[164:167], v[0:1], off offset:32
	global_load_dwordx4 v[168:171], v[0:1], off offset:64
	global_load_dwordx4 v[172:175], v[0:1], off offset:96
	global_load_dwordx4 v[176:179], v[0:1], off offset:128
	global_load_dwordx4 v[180:183], v[0:1], off offset:160
	global_load_dwordx4 v[184:187], v[0:1], off offset:192
	global_load_dwordx4 v[188:191], v[0:1], off offset:224
	s_lshl_b32 s22, s24, 3
	v_bfe_u32 v1, v2, 4, 2
	v_or_b32_e32 v0, s22, v1
	v_bitop3_b32 v4, v1, v2, 15 bitop3:0x78
	v_ashrrev_i32_e32 v1, 31, v0
	v_lshlrev_b64 v[212:213], 10, v[0:1]
	v_or_b32_e32 v0, 4, v0
	v_and_b32_e32 v3, 15, v2
	v_ashrrev_i32_e32 v1, 31, v0
	v_bitop3_b32 v3, v0, v3, 7 bitop3:0x6c
	v_lshlrev_b64 v[214:215], 10, v[0:1]
	v_bfe_u32 v0, v2, 2, 3
	v_bitop3_b32 v0, s22, -13, v0 bitop3:0xc8
	v_lshrrev_b32_e32 v1, 2, v2
	s_lshl_b32 s22, s24, 3
	v_and_b32_e32 v1, 4, v1
	s_and_b32 s22, s22, 8
	v_or3_b32 v0, v0, v1, s22
	s_add_i32 s21, s21, 0x24000
	v_ashrrev_i32_e32 v1, 31, v0
	v_lshlrev_b32_e32 v11, 3, v2
	s_lshl_b32 s22, s24, 11
	v_lshl_or_b32 v212, v4, 3, v212
	v_lshlrev_b64 v[216:217], 10, v[0:1]
	v_and_b32_e32 v0, 32, v2
	v_and_b32_e32 v1, 24, v11
	s_cmp_lg_u32 0, -1
	v_or3_b32 v216, v216, v1, v0
	v_lshlrev_b64 v[0:1], 1, v[212:213]
	s_cselect_b32 s23, 0, 0
	v_and_b32_e32 v10, 63, v2
	v_lshl_or_b32 v214, v3, 3, v214
	v_lshlrev_b32_e32 v12, 4, v2
	v_lshlrev_b32_e32 v13, 1, v2
	v_lshl_add_u64 v[2:3], s[0:1], 0, v[0:1]
	s_add_i32 s79, s22, s23
	s_mov_b32 s25, m0
	s_mov_b32 m0, s79
	s_nop 0
	global_load_lds_dwordx4 v[2:3], off
	s_mov_b32 m0, s25
	v_lshlrev_b64 v[2:3], 1, v[214:215]
	s_or_b32 s25, s22, 0x400
	v_lshl_add_u64 v[4:5], s[0:1], 0, v[2:3]
	s_add_i32 s81, s25, s23
	s_mov_b32 s84, m0
	s_mov_b32 m0, s81
	s_nop 0
	global_load_lds_dwordx4 v[4:5], off
	s_mov_b32 m0, s84
	s_lshl_b32 s24, s24, 12
	v_lshlrev_b64 v[4:5], 1, v[216:217]
	s_add_i32 s84, s23, 0xc000
	v_lshl_add_u64 v[6:7], s[14:15], 0, v[4:5]
	s_add_i32 s81, s24, s84
	s_mov_b32 s85, m0
	s_mov_b32 m0, s81
	s_nop 0
	global_load_lds_dwordx4 v[6:7], off
	s_mov_b32 m0, s85
	s_or_b32 s85, s24, 0x400
	s_add_i32 s86, s85, s84
	v_lshl_add_u64 v[8:9], v[6:7], 0, s[8:9]
	s_mov_b32 s87, m0
	s_mov_b32 m0, s86
	s_nop 0
	global_load_lds_dwordx4 v[8:9], off
	s_mov_b32 m0, s87
	s_or_b32 s86, s24, 0x800
	s_add_i32 s87, s86, s84
	v_lshl_add_u64 v[8:9], v[6:7], 0, s[10:11]
	s_mov_b32 s96, m0
	s_mov_b32 m0, s87
	s_nop 0
	global_load_lds_dwordx4 v[8:9], off
	s_mov_b32 m0, s96
	s_or_b32 s87, s24, 0xc00
	s_add_i32 s96, s87, s84
	s_add_u32 s0, s0, 0x20000
	v_lshl_add_u64 v[6:7], v[6:7], 0, s[12:13]
	s_mov_b32 s97, m0
	s_mov_b32 m0, s96
	s_nop 0
	global_load_lds_dwordx4 v[6:7], off
	s_mov_b32 m0, s97
	s_addc_u32 s1, s1, 0
	s_add_i32 s96, s23, 0x4000
	v_lshl_add_u64 v[0:1], s[0:1], 0, v[0:1]
	s_add_i32 s22, s22, s96
	s_mov_b32 s97, m0
	s_mov_b32 m0, s22
	s_nop 0
	global_load_lds_dwordx4 v[0:1], off
	s_mov_b32 m0, s97
	v_lshl_add_u64 v[0:1], s[0:1], 0, v[2:3]
	s_add_i32 s25, s25, s96
	s_mov_b32 s0, m0
	s_mov_b32 m0, s25
	s_nop 0
	global_load_lds_dwordx4 v[0:1], off
	s_mov_b32 m0, s0
	s_add_i32 s23, s23, 0x14000
	v_lshl_add_u64 v[0:1], s[16:17], 0, v[4:5]
	s_add_i32 s24, s24, s23
	s_mov_b32 s0, m0
	s_mov_b32 m0, s24
	s_nop 0
	global_load_lds_dwordx4 v[0:1], off
	s_mov_b32 m0, s0
	v_lshl_add_u64 v[2:3], v[0:1], 0, s[8:9]
	s_add_i32 s85, s85, s23
	s_mov_b32 s0, m0
	s_mov_b32 m0, s85
	s_nop 0
	global_load_lds_dwordx4 v[2:3], off
	s_mov_b32 m0, s0
	v_lshl_add_u64 v[2:3], v[0:1], 0, s[10:11]
	s_add_i32 s86, s86, s23
	s_mov_b32 s0, m0
	s_mov_b32 m0, s86
	s_nop 0
	global_load_lds_dwordx4 v[2:3], off
	s_mov_b32 m0, s0
	v_lshl_add_u64 v[0:1], v[0:1], 0, s[12:13]
	s_add_i32 s87, s87, s23
	s_mov_b32 s0, m0
	s_mov_b32 m0, s87
	s_nop 0
	global_load_lds_dwordx4 v[0:1], off
	s_mov_b32 m0, s0
	v_and_b32_e32 v0, 0x118, v11
	v_and_b32_e32 v14, 0xc0, v12
	s_movk_i32 s0, 0x70
	v_and_or_b32 v0, v13, 32, v0
	v_and_b32_e32 v1, 0x70, v12
	v_bitop3_b32 v221, v210, v12, s0 bitop3:0x78
	s_movk_i32 s0, 0xc0
	v_add3_u32 v230, v14, s84, v0
	v_mov_b32_e32 v14, v211
	v_mov_b32_e32 v15, v211
	v_bitop3_b32 v222, v210, v1, 32 bitop3:0x36
	v_bitop3_b32 v223, v210, v1, 64 bitop3:0x36
	v_bitop3_b32 v225, v210, v1, s38 bitop3:0x36
	v_bitop3_b32 v226, v210, v1, s39 bitop3:0x36
	v_bitop3_b32 v227, v210, v1, s40 bitop3:0x36
	v_bitop3_b32 v228, v210, v1, s0 bitop3:0x36
	v_bitop3_b32 v229, v210, v1, s41 bitop3:0x36
	v_cmp_gt_u32_e64 s[0:1], 32, v10
	s_add_u32 s84, s74, s4
	v_mov_b32_e32 v0, v211
	v_mov_b32_e32 v1, v211
	v_mov_b32_e32 v2, v211
	v_mov_b32_e32 v3, v211
	v_mov_b32_e32 v4, v211
	v_mov_b32_e32 v5, v211
	v_mov_b32_e32 v6, v211
	v_mov_b32_e32 v7, v211
	v_mov_b32_e32 v8, v211
	v_mov_b32_e32 v9, v211
	v_mov_b32_e32 v10, v211
	v_mov_b32_e32 v11, v211
	v_mov_b32_e32 v12, v211
	v_mov_b32_e32 v13, v211
	v_mov_b64_e32 v[126:127], v[14:15]
	v_mov_b64_e32 v[110:111], v[14:15]
	v_mov_b64_e32 v[94:95], v[14:15]
	v_mov_b64_e32 v[78:79], v[14:15]
	v_mov_b64_e32 v[62:63], v[14:15]
	v_mov_b64_e32 v[46:47], v[14:15]
	v_mov_b64_e32 v[30:31], v[14:15]
	s_mov_b32 s78, 2
	s_mov_b32 s80, 0
	v_lshlrev_b32_e32 v220, 8, v219
	v_lshl_add_u32 v224, v219, 2, s21
	s_addc_u32 s85, s75, s5
	v_mov_b32_e32 v232, 0
	v_mov_b32_e32 v231, 0xf149f2ca
	s_mov_b64 s[22:23], 0
	v_mov_b64_e32 v[124:125], v[12:13]
	v_mov_b64_e32 v[122:123], v[10:11]
	v_mov_b64_e32 v[120:121], v[8:9]
	v_mov_b64_e32 v[118:119], v[6:7]
	v_mov_b64_e32 v[116:117], v[4:5]
	v_mov_b64_e32 v[114:115], v[2:3]
	v_mov_b64_e32 v[112:113], v[0:1]
	v_mov_b64_e32 v[108:109], v[12:13]
	v_mov_b64_e32 v[106:107], v[10:11]
	v_mov_b64_e32 v[104:105], v[8:9]
	v_mov_b64_e32 v[102:103], v[6:7]
	v_mov_b64_e32 v[100:101], v[4:5]
	v_mov_b64_e32 v[98:99], v[2:3]
	v_mov_b64_e32 v[96:97], v[0:1]
	v_mov_b64_e32 v[92:93], v[12:13]
	v_mov_b64_e32 v[90:91], v[10:11]
	v_mov_b64_e32 v[88:89], v[8:9]
	v_mov_b64_e32 v[86:87], v[6:7]
	v_mov_b64_e32 v[84:85], v[4:5]
	v_mov_b64_e32 v[82:83], v[2:3]
	v_mov_b64_e32 v[80:81], v[0:1]
	v_mov_b64_e32 v[76:77], v[12:13]
	v_mov_b64_e32 v[74:75], v[10:11]
	v_mov_b64_e32 v[72:73], v[8:9]
	v_mov_b64_e32 v[70:71], v[6:7]
	v_mov_b64_e32 v[68:69], v[4:5]
	v_mov_b64_e32 v[66:67], v[2:3]
	v_mov_b64_e32 v[64:65], v[0:1]
	v_mov_b64_e32 v[60:61], v[12:13]
	v_mov_b64_e32 v[58:59], v[10:11]
	v_mov_b64_e32 v[56:57], v[8:9]
	v_mov_b64_e32 v[54:55], v[6:7]
	v_mov_b64_e32 v[52:53], v[4:5]
	v_mov_b64_e32 v[50:51], v[2:3]
	v_mov_b64_e32 v[48:49], v[0:1]
	v_mov_b64_e32 v[44:45], v[12:13]
	v_mov_b64_e32 v[42:43], v[10:11]
	v_mov_b64_e32 v[40:41], v[8:9]
	v_mov_b64_e32 v[38:39], v[6:7]
	v_mov_b64_e32 v[36:37], v[4:5]
	v_mov_b64_e32 v[34:35], v[2:3]
	v_mov_b64_e32 v[32:33], v[0:1]
	v_mov_b64_e32 v[28:29], v[12:13]
	v_mov_b64_e32 v[26:27], v[10:11]
	v_mov_b64_e32 v[24:25], v[8:9]
	v_mov_b64_e32 v[22:23], v[6:7]
	v_mov_b64_e32 v[20:21], v[4:5]
	v_mov_b64_e32 v[18:19], v[2:3]
	v_mov_b64_e32 v[16:17], v[0:1]
	s_mov_b32 s86, 0
	s_cmp_eq_u32 s22, 0x7e0000
	s_mov_b64 s[4:5], -1
	s_cbranch_scc0 .LBB0_912

.LBB0_910:
	v_cndmask_b32_e64 v231, v234, v231, s[4:5]
	v_mul_f32_e32 v192, 0xbe0293ee, v231
	v_fmamk_f32 v144, v144, 0x3e0293ee, v192
	v_fmamk_f32 v145, v145, 0x3e0293ee, v192
	v_fmamk_f32 v146, v146, 0x3e0293ee, v192
	v_fmamk_f32 v147, v147, 0x3e0293ee, v192
	v_fmamk_f32 v148, v148, 0x3e0293ee, v192
	v_fmamk_f32 v149, v149, 0x3e0293ee, v192
	v_fmamk_f32 v150, v150, 0x3e0293ee, v192
	v_fmamk_f32 v151, v151, 0x3e0293ee, v192
	v_fmamk_f32 v152, v152, 0x3e0293ee, v192
	v_fmamk_f32 v153, v153, 0x3e0293ee, v192
	v_fmamk_f32 v154, v154, 0x3e0293ee, v192
	v_fmamk_f32 v155, v155, 0x3e0293ee, v192
	v_fmamk_f32 v156, v156, 0x3e0293ee, v192
	v_fmamk_f32 v157, v157, 0x3e0293ee, v192
	v_fmamk_f32 v158, v158, 0x3e0293ee, v192
	v_fmamk_f32 v159, v159, 0x3e0293ee, v192
	v_fmamk_f32 v128, v128, 0x3e0293ee, v192
	v_fmamk_f32 v129, v129, 0x3e0293ee, v192
	v_fmamk_f32 v130, v130, 0x3e0293ee, v192
	v_fmamk_f32 v131, v131, 0x3e0293ee, v192
	v_fmamk_f32 v132, v132, 0x3e0293ee, v192
	v_fmamk_f32 v133, v133, 0x3e0293ee, v192
	v_fmamk_f32 v134, v134, 0x3e0293ee, v192
	v_fmamk_f32 v135, v135, 0x3e0293ee, v192
	v_fmamk_f32 v136, v136, 0x3e0293ee, v192
	v_fmamk_f32 v137, v137, 0x3e0293ee, v192
	v_fmamk_f32 v138, v138, 0x3e0293ee, v192
	v_fmamk_f32 v139, v139, 0x3e0293ee, v192
	v_fmamk_f32 v140, v140, 0x3e0293ee, v192
	v_fmamk_f32 v141, v141, 0x3e0293ee, v192
	v_fmamk_f32 v142, v142, 0x3e0293ee, v192
	v_fmac_f32_e32 v192, 0x3e0293ee, v143
	v_exp_f32_e32 v143, v144
	v_exp_f32_e32 v145, v145
	v_exp_f32_e32 v146, v146
	v_exp_f32_e32 v147, v147
	v_exp_f32_e32 v148, v148
	v_exp_f32_e32 v193, v128
	v_exp_f32_e32 v149, v149
	v_add_f32_e32 v128, v145, v143
	v_exp_f32_e32 v150, v150
	v_add_f32_e32 v128, v146, v128
	v_exp_f32_e32 v151, v151
	v_add_f32_e32 v128, v147, v128
	v_exp_f32_e32 v152, v152
	v_add_f32_e32 v128, v148, v128
	v_exp_f32_e32 v153, v153
	v_add_f32_e32 v128, v149, v128
	v_exp_f32_e32 v154, v154
	v_add_f32_e32 v128, v150, v128
	v_exp_f32_e32 v155, v155
	v_add_f32_e32 v128, v151, v128
	v_exp_f32_e32 v156, v156
	v_add_f32_e32 v128, v152, v128
	v_exp_f32_e32 v157, v157
	v_add_f32_e32 v128, v153, v128
	v_exp_f32_e32 v158, v158
	v_add_f32_e32 v128, v154, v128
	v_exp_f32_e32 v159, v159
	v_add_f32_e32 v128, v155, v128
	v_add_f32_e32 v128, v156, v128
	v_exp_f32_e32 v194, v129
	v_add_f32_e32 v128, v157, v128
	v_exp_f32_e32 v195, v130
	v_add_f32_e32 v128, v158, v128
	v_exp_f32_e32 v196, v131
	v_add_f32_e32 v128, v159, v128
	v_exp_f32_e32 v197, v132
	v_add_f32_e32 v128, v193, v128
	v_exp_f32_e32 v198, v133
	v_add_f32_e32 v128, v194, v128
	v_exp_f32_e32 v199, v134
	v_add_f32_e32 v128, v195, v128
	v_exp_f32_e32 v135, v135
	v_add_f32_e32 v128, v196, v128
	v_exp_f32_e32 v200, v136
	v_add_f32_e32 v128, v197, v128
	v_exp_f32_e32 v201, v137
	v_add_f32_e32 v128, v198, v128
	v_exp_f32_e32 v202, v138
	v_add_f32_e32 v128, v199, v128
	v_exp_f32_e32 v203, v139
	v_add_f32_e32 v128, v135, v128
	v_exp_f32_e32 v204, v140
	v_add_f32_e32 v128, v200, v128
	v_exp_f32_e32 v205, v141
	v_add_f32_e32 v128, v201, v128
	v_exp_f32_e32 v206, v142
	v_add_f32_e32 v128, v202, v128
	v_exp_f32_e32 v192, v192
	v_add_f32_e32 v128, v203, v128
	v_add_f32_e32 v128, v204, v128
	v_add_f32_e32 v128, v205, v128
	v_add_f32_e32 v128, v206, v128
	v_add_f32_e32 v128, v192, v128
	v_mov_b32_e32 v129, v128
	s_nop 1
	v_permlane32_swap_b32_e32 v128, v129
	v_add_f32_e32 v144, v128, v129
	v_fmac_f32_e32 v144, v232, v233
	v_cvt_pk_bf16_f32 v128, v143, v145
	v_cvt_pk_bf16_f32 v129, v146, v147
	v_cvt_pk_bf16_f32 v130, v148, v149
	v_cvt_pk_bf16_f32 v131, v150, v151
	v_cvt_pk_bf16_f32 v136, v152, v153
	v_cvt_pk_bf16_f32 v137, v154, v155
	v_cvt_pk_bf16_f32 v138, v156, v157
	v_cvt_pk_bf16_f32 v139, v158, v159
	v_cvt_pk_bf16_f32 v132, v193, v194
	v_cvt_pk_bf16_f32 v133, v195, v196
	v_cvt_pk_bf16_f32 v134, v197, v198
	v_cvt_pk_bf16_f32 v135, v199, v135
	v_cvt_pk_bf16_f32 v140, v200, v201
	v_cvt_pk_bf16_f32 v141, v202, v203
	v_cvt_pk_bf16_f32 v142, v204, v205
	v_cvt_pk_bf16_f32 v143, v206, v192
	v_lshl_add_u32 v145, s80, 15, v230
	ds_read_b64_tr_b16 v[146:147], v145 offset:0
	ds_read_b64_tr_b16 v[148:149], v145 offset:0x1000
	ds_read_b64_tr_b16 v[150:151], v145 offset:0x2000
	ds_read_b64_tr_b16 v[152:153], v145 offset:0x3000
	ds_read_b64_tr_b16 v[154:155], v145 offset:0x4000
	ds_read_b64_tr_b16 v[156:157], v145 offset:0x5000
	ds_read_b64_tr_b16 v[192:193], v145 offset:0x6000
	ds_read_b64_tr_b16 v[194:195], v145 offset:0x7000
	ds_read_b64_tr_b16 v[196:197], v145 offset:0x200
	ds_read_b64_tr_b16 v[198:199], v145 offset:0x1200
	ds_read_b64_tr_b16 v[200:201], v145 offset:0x2200
	ds_read_b64_tr_b16 v[202:203], v145 offset:0x3200
	ds_read_b64_tr_b16 v[204:205], v145 offset:0x4200
	ds_read_b64_tr_b16 v[206:207], v145 offset:0x5200
	ds_read_b64_tr_b16 v[232:233], v145 offset:0x6200
	ds_read_b64_tr_b16 v[234:235], v145 offset:0x7200
	s_waitcnt lgkmcnt(8)
	s_nop 0
	v_mfma_f32_32x32x16_bf16 v[0:15], v[128:131], v[146:149], v[0:15]
	v_mfma_f32_32x32x16_bf16 v[0:15], v[136:139], v[150:153], v[0:15]
	v_mfma_f32_32x32x16_bf16 v[0:15], v[132:135], v[154:157], v[0:15]
	v_mfma_f32_32x32x16_bf16 v[0:15], v[140:143], v[192:195], v[0:15]
	ds_read_b64_tr_b16 v[146:147], v145 offset:0x400
	ds_read_b64_tr_b16 v[148:149], v145 offset:0x1400
	ds_read_b64_tr_b16 v[150:151], v145 offset:0x2400
	ds_read_b64_tr_b16 v[152:153], v145 offset:0x3400
	ds_read_b64_tr_b16 v[154:155], v145 offset:0x4400
	ds_read_b64_tr_b16 v[156:157], v145 offset:0x5400
	ds_read_b64_tr_b16 v[192:193], v145 offset:0x6400
	ds_read_b64_tr_b16 v[194:195], v145 offset:0x7400
	s_waitcnt lgkmcnt(8)
	v_mfma_f32_32x32x16_bf16 v[112:127], v[128:131], v[196:199], v[112:127]
	v_mfma_f32_32x32x16_bf16 v[112:127], v[136:139], v[200:203], v[112:127]
	v_mfma_f32_32x32x16_bf16 v[112:127], v[132:135], v[204:207], v[112:127]
	v_mfma_f32_32x32x16_bf16 v[112:127], v[140:143], v[232:235], v[112:127]
	ds_read_b64_tr_b16 v[196:197], v145 offset:0x600
	ds_read_b64_tr_b16 v[198:199], v145 offset:0x1600
	ds_read_b64_tr_b16 v[200:201], v145 offset:0x2600
	ds_read_b64_tr_b16 v[202:203], v145 offset:0x3600
	ds_read_b64_tr_b16 v[204:205], v145 offset:0x4600
	ds_read_b64_tr_b16 v[206:207], v145 offset:0x5600
	ds_read_b64_tr_b16 v[232:233], v145 offset:0x6600
	ds_read_b64_tr_b16 v[234:235], v145 offset:0x7600
	s_waitcnt lgkmcnt(8)
	v_mfma_f32_32x32x16_bf16 v[96:111], v[128:131], v[146:149], v[96:111]
	v_mfma_f32_32x32x16_bf16 v[96:111], v[136:139], v[150:153], v[96:111]
	v_mfma_f32_32x32x16_bf16 v[96:111], v[132:135], v[154:157], v[96:111]
	v_mfma_f32_32x32x16_bf16 v[96:111], v[140:143], v[192:195], v[96:111]
	ds_read_b64_tr_b16 v[146:147], v145 offset:0x800
	ds_read_b64_tr_b16 v[148:149], v145 offset:0x1800
	ds_read_b64_tr_b16 v[150:151], v145 offset:0x2800
	ds_read_b64_tr_b16 v[152:153], v145 offset:0x3800
	ds_read_b64_tr_b16 v[154:155], v145 offset:0x4800
	ds_read_b64_tr_b16 v[156:157], v145 offset:0x5800
	ds_read_b64_tr_b16 v[192:193], v145 offset:0x6800
	ds_read_b64_tr_b16 v[194:195], v145 offset:0x7800
	s_waitcnt lgkmcnt(8)
	v_mfma_f32_32x32x16_bf16 v[80:95], v[128:131], v[196:199], v[80:95]
	v_mfma_f32_32x32x16_bf16 v[80:95], v[136:139], v[200:203], v[80:95]
	v_mfma_f32_32x32x16_bf16 v[80:95], v[132:135], v[204:207], v[80:95]
	v_mfma_f32_32x32x16_bf16 v[80:95], v[140:143], v[232:235], v[80:95]
	ds_read_b64_tr_b16 v[196:197], v145 offset:0xa00
	ds_read_b64_tr_b16 v[198:199], v145 offset:0x1a00
	ds_read_b64_tr_b16 v[200:201], v145 offset:0x2a00
	ds_read_b64_tr_b16 v[202:203], v145 offset:0x3a00
	ds_read_b64_tr_b16 v[204:205], v145 offset:0x4a00
	ds_read_b64_tr_b16 v[206:207], v145 offset:0x5a00
	ds_read_b64_tr_b16 v[232:233], v145 offset:0x6a00
	ds_read_b64_tr_b16 v[234:235], v145 offset:0x7a00
	s_waitcnt lgkmcnt(8)
	v_mfma_f32_32x32x16_bf16 v[64:79], v[128:131], v[146:149], v[64:79]
	v_mfma_f32_32x32x16_bf16 v[64:79], v[136:139], v[150:153], v[64:79]
	v_mfma_f32_32x32x16_bf16 v[64:79], v[132:135], v[154:157], v[64:79]
	v_mfma_f32_32x32x16_bf16 v[64:79], v[140:143], v[192:195], v[64:79]
	ds_read_b64_tr_b16 v[146:147], v145 offset:0xc00
	ds_read_b64_tr_b16 v[148:149], v145 offset:0x1c00
	ds_read_b64_tr_b16 v[150:151], v145 offset:0x2c00
	ds_read_b64_tr_b16 v[152:153], v145 offset:0x3c00
	ds_read_b64_tr_b16 v[154:155], v145 offset:0x4c00
	ds_read_b64_tr_b16 v[156:157], v145 offset:0x5c00
	ds_read_b64_tr_b16 v[192:193], v145 offset:0x6c00
	ds_read_b64_tr_b16 v[194:195], v145 offset:0x7c00
	s_waitcnt lgkmcnt(8)
	v_mfma_f32_32x32x16_bf16 v[48:63], v[128:131], v[196:199], v[48:63]
	v_mfma_f32_32x32x16_bf16 v[48:63], v[136:139], v[200:203], v[48:63]
	v_mfma_f32_32x32x16_bf16 v[48:63], v[132:135], v[204:207], v[48:63]
	v_mfma_f32_32x32x16_bf16 v[48:63], v[140:143], v[232:235], v[48:63]
	ds_read_b64_tr_b16 v[196:197], v145 offset:0xe00
	ds_read_b64_tr_b16 v[198:199], v145 offset:0x1e00
	ds_read_b64_tr_b16 v[200:201], v145 offset:0x2e00
	ds_read_b64_tr_b16 v[202:203], v145 offset:0x3e00
	ds_read_b64_tr_b16 v[204:205], v145 offset:0x4e00
	ds_read_b64_tr_b16 v[206:207], v145 offset:0x5e00
	ds_read_b64_tr_b16 v[232:233], v145 offset:0x6e00
	ds_read_b64_tr_b16 v[234:235], v145 offset:0x7e00
	s_waitcnt lgkmcnt(8)
	v_mfma_f32_32x32x16_bf16 v[32:47], v[128:131], v[146:149], v[32:47]
	v_mfma_f32_32x32x16_bf16 v[32:47], v[136:139], v[150:153], v[32:47]
	v_mfma_f32_32x32x16_bf16 v[32:47], v[132:135], v[154:157], v[32:47]
	v_mfma_f32_32x32x16_bf16 v[32:47], v[140:143], v[192:195], v[32:47]
	s_waitcnt lgkmcnt(0)
	v_mfma_f32_32x32x16_bf16 v[16:31], v[128:131], v[196:199], v[16:31]
	s_add_i32 s4, s80, 1
	s_cmp_lg_u32 s80, 2
	s_cselect_b32 s80, s4, 0
	s_add_i32 s4, s78, 1
	s_cmp_lg_u32 s78, 2
	s_cselect_b32 s78, s4, 0
	s_add_u32 s22, s22, 0x20000
	v_mfma_f32_32x32x16_bf16 v[16:31], v[136:139], v[200:203], v[16:31]
	s_addc_u32 s23, s23, 0
	s_add_i32 s86, s86, 1
	s_cmp_eq_u32 s22, 0x800000
	v_mfma_f32_32x32x16_bf16 v[16:31], v[132:135], v[204:207], v[16:31]
	v_mfma_f32_32x32x16_bf16 v[16:31], v[140:143], v[232:235], v[16:31]
	s_cbranch_scc1 .LBB0_914
	v_mov_b32_e32 v232, v144
	s_cmp_eq_u32 s22, 0x7e0000
	s_mov_b64 s[4:5], -1
	s_cbranch_scc1 .LBB0_903
